# version 97 plus gate|up and in-proj: the peeled first K-iteration of a continuing unit waits vmcnt(16) instead of 8 in its second load segment (does not force the previous epilogue's stores to retire)
# baseline (speedup 1.0000x reference)
; #define PG8_STAGE(bufoff, gbase, voff) do { _Pragma("unroll") for (int _i = 0; _i < 2; ++_i) \
;         __builtin_amdgcn_global_load_lds((const unsigned*)((const char*)(gbase) + (voff)[_i]), (PG8_LAS unsigned*)(lds + (bufoff) + ldsw + _i * 8192), 16, 0, 0); } while (0)
; #define PG8_LDA(dst, b, h) do { _Pragma("unroll") for (int m = 0; m < 4; ++m) _Pragma("unroll") for (int k = 0; k < 2; ++k) dst[m][k] = *(const PG8_LAS bf16x8*)(lds + PG8_SA(b, h) + aoff + m * 2048 + k * 1024); } while (0)
; #define PG8_LDB(dst, b, h) do { _Pragma("unroll") for (int n = 0; n < 2; ++n) _Pragma("unroll") for (int k = 0; k < 2; ++k) dst[n][k] = *(const PG8_LAS bf16x8*)(lds + PG8_SB(b, h) + boff + n * 2048 + k * 1024); } while (0)
; #define PG8_WAIT_V(n) asm volatile("s_waitcnt vmcnt(" #n ")" ::: "memory")
; #define PG8_WAIT_L(n) asm volatile("s_waitcnt lgkmcnt(" #n ")" ::: "memory")
; #define PG8_BAR __builtin_amdgcn_s_barrier()
; #define PG8_SCHED __builtin_amdgcn_sched_barrier(0)
; template <class Epi, class Sched, bool ALIGN_EPI = false, bool SP2 = false>
; __device__ __forceinline__ void gemm_phase(PG8_LAS unsigned char* lds, const Gemm g, const Sched& S, const Epi& E, const int tid_in) {
;     ...
;         const char* nA = has_next ? (const char*)g.A + (size_t)nxt.pm * tstep : cA; const char* nB = has_next ? (const char*)g.Bt + (size_t)nxt.pn * tstep : cB;
;         for (int t = 0; t < nt; t += 2) {
;             const bool last = (t == nt - 2);
;             const char* a1 = cA + (size_t)(t + 1) * kstep;
;             const char* a2 = last ? nA : cA + (size_t)(t + 2) * kstep; const char* b2 = last ? nB : cB + (size_t)(t + 2) * kstep;
;             const char* a3 = a2 + kstep; const char* b3 = b2 + kstep;
;             if (last && has_next) S.a_ready(nxt);
;             if constexpr (SP2) {
;             PG8_LDB(B0, 0, 0); PG8_LDB(B1, 0, 1); PG8_SCHED; PG8_LDA(At, 0, 0); PG8_STAGE(PG8_SA(1, 1), a1 + hstep, voffA);
;             PG8_WAIT_V(8); PG8_WAIT_L(0); PG8_BAR; PG8_MMA(0, 0, At, B0); PG8_MMA(0, 1, At, B1); PG8_BAR; PG8_SCHED;
;             PG8_LDA(At, 0, 1); PG8_STAGE(PG8_SB(0, 0), b2, voffB); PG8_STAGE(PG8_SB(0, 1), b2 + hstep, voffB); PG8_STAGE(PG8_SA(0, 0), a2, voffA);
;             PG8_WAIT_V(8); PG8_WAIT_L(0); PG8_BAR; PG8_MMA(1, 0, At, B0); PG8_MMA(1, 1, At, B1); PG8_BAR; PG8_SCHED;
.LBB0_92:
	s_ashr_i32 s25, s24, 31
	s_lshl_b64 s[16:17], s[24:25], 19
	s_add_u32 s34, s84, s16
	s_addc_u32 s35, s85, s17
	s_and_b64 s[16:17], s[36:37], exec
	s_cselect_b32 s11, s35, s15
	s_cselect_b32 s16, s34, s14
	s_ashr_i32 s21, s20, 31
	s_lshl_b64 s[40:41], s[20:21], 19
	s_add_u32 s40, s3, s40
	s_addc_u32 s41, s18, s41
	s_and_b64 s[42:43], s[36:37], exec
	s_cselect_b32 s17, s41, s13
	s_cselect_b32 s21, s40, s12
	s_add_u32 s42, s14, 0x40080
	s_addc_u32 s43, s15, 0
	s_add_u32 s25, s12, 0x100
	s_addc_u32 s39, s13, 0
	s_mov_b32 s45, -2
	s_add_u32 s12, s42, 0xfffc0080
	s_addc_u32 s13, s43, -1
	s_add_i32 s46, 0, 0x10000
	s_cmp_eq_u32 s45, 12
	s_cselect_b32 s15, s11, s13
	s_cselect_b32 s14, s16, s12
	v_add_u32_e32 v148, s46, v150
	s_cselect_b32 s13, s17, s39
	s_cselect_b32 s12, s21, s25
	s_add_i32 s48, 0, 0x14000
	ds_read_b128 v[144:147], v148
	ds_read_b128 v[154:157], v148 offset:1024
	ds_read_b128 v[158:161], v148 offset:2048
	ds_read_b128 v[162:165], v148 offset:3072
	v_add_u32_e32 v148, s48, v150
	ds_read_b128 v[166:169], v148
	ds_read_b128 v[170:173], v148 offset:1024
	ds_read_b128 v[174:177], v148 offset:2048
	ds_read_b128 v[178:181], v148 offset:3072
	v_lshl_add_u64 v[148:149], s[42:43], 0, v[140:141]
	s_add_i32 m0, s22, 0xc000
	ds_read_b128 v[182:185], v152
	ds_read_b128 v[186:189], v152 offset:1024
	ds_read_b128 v[190:193], v152 offset:2048
	ds_read_b128 v[198:201], v152 offset:3072
	ds_read_b128 v[202:205], v152 offset:4096
	ds_read_b128 v[206:209], v152 offset:5120
	ds_read_b128 v[210:213], v152 offset:6144
	ds_read_b128 v[214:217], v152 offset:7168
	global_load_lds_dwordx4 v[148:149], off
	v_lshl_add_u64 v[148:149], s[42:43], 0, v[142:143]
	s_add_i32 m0, s22, 0xe000
	s_nop 0
	global_load_lds_dwordx4 v[148:149], off
	s_nop 0
	s_waitcnt vmcnt(8)
	s_waitcnt lgkmcnt(0)
	s_barrier
	v_mfma_f32_16x16x32_bf16 v[130:133], v[144:147], v[182:185], 0
	v_mfma_f32_16x16x32_bf16 v[130:133], v[154:157], v[186:189], v[130:133]
	v_mfma_f32_16x16x32_bf16 v[114:117], v[144:147], v[190:193], 0
	v_mfma_f32_16x16x32_bf16 v[114:117], v[154:157], v[198:201], v[114:117]
	v_mfma_f32_16x16x32_bf16 v[98:101], v[144:147], v[202:205], 0
	v_mfma_f32_16x16x32_bf16 v[98:101], v[154:157], v[206:209], v[98:101]
	v_mfma_f32_16x16x32_bf16 v[82:85], v[144:147], v[210:213], 0
	v_mfma_f32_16x16x32_bf16 v[82:85], v[154:157], v[214:217], v[82:85]
	v_mfma_f32_16x16x32_bf16 v[126:129], v[158:161], v[182:185], 0
	v_mfma_f32_16x16x32_bf16 v[126:129], v[162:165], v[186:189], v[126:129]
	v_mfma_f32_16x16x32_bf16 v[110:113], v[158:161], v[190:193], 0
	v_mfma_f32_16x16x32_bf16 v[110:113], v[162:165], v[198:201], v[110:113]
	v_mfma_f32_16x16x32_bf16 v[94:97], v[158:161], v[202:205], 0
	v_mfma_f32_16x16x32_bf16 v[94:97], v[162:165], v[206:209], v[94:97]
	v_mfma_f32_16x16x32_bf16 v[78:81], v[158:161], v[210:213], 0
	v_mfma_f32_16x16x32_bf16 v[78:81], v[162:165], v[214:217], v[78:81]
	v_mfma_f32_16x16x32_bf16 v[122:125], v[166:169], v[182:185], 0
	v_mfma_f32_16x16x32_bf16 v[122:125], v[170:173], v[186:189], v[122:125]
	v_mfma_f32_16x16x32_bf16 v[106:109], v[166:169], v[190:193], 0
	v_mfma_f32_16x16x32_bf16 v[106:109], v[170:173], v[198:201], v[106:109]
	v_mfma_f32_16x16x32_bf16 v[90:93], v[166:169], v[202:205], 0
	v_mfma_f32_16x16x32_bf16 v[90:93], v[170:173], v[206:209], v[90:93]
	v_mfma_f32_16x16x32_bf16 v[74:77], v[166:169], v[210:213], 0
	v_mfma_f32_16x16x32_bf16 v[74:77], v[170:173], v[214:217], v[74:77]
	v_mfma_f32_16x16x32_bf16 v[118:121], v[174:177], v[182:185], 0
	v_mfma_f32_16x16x32_bf16 v[118:121], v[178:181], v[186:189], v[118:121]
	v_mfma_f32_16x16x32_bf16 v[102:105], v[174:177], v[190:193], 0
	v_mfma_f32_16x16x32_bf16 v[102:105], v[178:181], v[198:201], v[102:105]
	v_mfma_f32_16x16x32_bf16 v[86:89], v[174:177], v[202:205], 0
	v_mfma_f32_16x16x32_bf16 v[86:89], v[178:181], v[206:209], v[86:89]
	v_mfma_f32_16x16x32_bf16 v[70:73], v[174:177], v[210:213], 0
	v_mfma_f32_16x16x32_bf16 v[70:73], v[178:181], v[214:217], v[70:73]
	s_barrier
	s_add_i32 s46, s46, s19
	v_lshl_add_u64 v[148:149], s[12:13], 0, v[134:135]
	s_mov_b32 m0, s46
	ds_read_b128 v[182:185], v152 offset:16384
	ds_read_b128 v[186:189], v152 offset:17408
	ds_read_b128 v[190:193], v152 offset:18432
	ds_read_b128 v[198:201], v152 offset:19456
	ds_read_b128 v[202:205], v152 offset:20480
	ds_read_b128 v[206:209], v152 offset:21504
	ds_read_b128 v[210:213], v152 offset:22528
	ds_read_b128 v[214:217], v152 offset:23552
	global_load_lds_dwordx4 v[148:149], off
	s_add_i32 m0, s46, 0x2000
	s_add_u32 s46, s12, 0x40000
	v_lshl_add_u64 v[218:219], s[12:13], 0, v[138:139]
	s_addc_u32 s47, s13, 0
	s_add_i32 s48, s48, s19
	global_load_lds_dwordx4 v[218:219], off
	v_lshl_add_u64 v[220:221], s[46:47], 0, v[134:135]
	s_mov_b32 m0, s48
	v_lshl_add_u64 v[222:223], s[14:15], 0, v[136:137]
	global_load_lds_dwordx4 v[220:221], off
	v_lshl_add_u64 v[220:221], s[46:47], 0, v[138:139]
	s_add_i32 m0, s48, 0x2000
	s_nop 0
	global_load_lds_dwordx4 v[220:221], off
	v_lshl_add_u64 v[220:221], s[14:15], 0, v[2:3]
	s_mov_b32 m0, s22
	s_nop 0
	global_load_lds_dwordx4 v[220:221], off
	s_mov_b32 m0, s23
	s_nop 0
	global_load_lds_dwordx4 v[222:223], off
	s_cmp_lt_u32 s44, 2
	s_cbranch_scc1 .Lpwin_first
	s_waitcnt vmcnt(16)
	s_branch .Lpwin_j

; #define PG8_STAGE(bufoff, gbase, voff) do { _Pragma("unroll") for (int _i = 0; _i < 2; ++_i) \
;         __builtin_amdgcn_global_load_lds((const unsigned*)((const char*)(gbase) + (voff)[_i]), (PG8_LAS unsigned*)(lds + (bufoff) + ldsw + _i * 8192), 16, 0, 0); } while (0)
; #define PG8_LDA(dst, b, h) do { _Pragma("unroll") for (int m = 0; m < 4; ++m) _Pragma("unroll") for (int k = 0; k < 2; ++k) dst[m][k] = *(const PG8_LAS bf16x8*)(lds + PG8_SA(b, h) + aoff + m * 2048 + k * 1024); } while (0)
; #define PG8_LDB(dst, b, h) do { _Pragma("unroll") for (int n = 0; n < 2; ++n) _Pragma("unroll") for (int k = 0; k < 2; ++k) dst[n][k] = *(const PG8_LAS bf16x8*)(lds + PG8_SB(b, h) + boff + n * 2048 + k * 1024); } while (0)
; #define PG8_MMA(ai, bj, At, Bt) do { __builtin_amdgcn_s_setprio(1); _Pragma("unroll") for (int m = 0; m < 4; ++m) _Pragma("unroll") for (int n = 0; n < 2; ++n) _Pragma("unroll") for (int k = 0; k < 2; ++k) \
;         acc[ai][bj][m][n] = __builtin_amdgcn_mfma_f32_16x16x32_bf16(Bt[n][k], At[m][k], acc[ai][bj][m][n], 0, 0, 0); __builtin_amdgcn_s_setprio(0); } while (0)
; #define PG8_WAIT_V(n) asm volatile("s_waitcnt vmcnt(" #n ")" ::: "memory")
; #define PG8_WAIT_L(n) asm volatile("s_waitcnt lgkmcnt(" #n ")" ::: "memory")
; #define PG8_BAR __builtin_amdgcn_s_barrier()
; #define PG8_SCHED __builtin_amdgcn_sched_barrier(0)
; template <class Epi, class Sched, bool ALIGN_EPI = false, bool SP2 = false>
; __device__ __forceinline__ void gemm_phase(PG8_LAS unsigned char* lds, const Gemm g, const Sched& S, const Epi& E, const int tid_in) {
;     ...
;             PG8_WAIT_V(8); PG8_WAIT_L(0); PG8_BAR; PG8_MMA(1, 0, At, B0); PG8_MMA(1, 1, At, B1); PG8_BAR; PG8_SCHED;
;             PG8_LDB(B0, 1, 0); PG8_LDB(B1, 1, 1); PG8_SCHED; PG8_LDA(At, 1, 0); PG8_STAGE(PG8_SA(0, 1), a2 + hstep, voffA);
;             PG8_WAIT_V(8); PG8_WAIT_L(0); PG8_BAR; PG8_MMA(0, 0, At, B0); PG8_MMA(0, 1, At, B1); PG8_BAR; PG8_SCHED;
.Lpwin_j:
	s_waitcnt lgkmcnt(0)
	s_barrier
	v_mfma_f32_16x16x32_bf16 v[66:69], v[144:147], v[182:185], 0
	v_mfma_f32_16x16x32_bf16 v[66:69], v[154:157], v[186:189], v[66:69]
	v_mfma_f32_16x16x32_bf16 v[50:53], v[144:147], v[190:193], 0
	v_mfma_f32_16x16x32_bf16 v[50:53], v[154:157], v[198:201], v[50:53]
	v_mfma_f32_16x16x32_bf16 v[34:37], v[144:147], v[202:205], 0
	v_mfma_f32_16x16x32_bf16 v[34:37], v[154:157], v[206:209], v[34:37]
	v_mfma_f32_16x16x32_bf16 v[18:21], v[144:147], v[210:213], 0
	v_mfma_f32_16x16x32_bf16 v[18:21], v[154:157], v[214:217], v[18:21]
	v_mfma_f32_16x16x32_bf16 v[62:65], v[158:161], v[182:185], 0
	v_mfma_f32_16x16x32_bf16 v[62:65], v[162:165], v[186:189], v[62:65]
	v_mfma_f32_16x16x32_bf16 v[46:49], v[158:161], v[190:193], 0
	v_mfma_f32_16x16x32_bf16 v[46:49], v[162:165], v[198:201], v[46:49]
	v_mfma_f32_16x16x32_bf16 v[30:33], v[158:161], v[202:205], 0
	v_mfma_f32_16x16x32_bf16 v[30:33], v[162:165], v[206:209], v[30:33]
	v_mfma_f32_16x16x32_bf16 v[14:17], v[158:161], v[210:213], 0
	v_mfma_f32_16x16x32_bf16 v[14:17], v[162:165], v[214:217], v[14:17]
	v_mfma_f32_16x16x32_bf16 v[58:61], v[166:169], v[182:185], 0
	v_mfma_f32_16x16x32_bf16 v[58:61], v[170:173], v[186:189], v[58:61]
	v_mfma_f32_16x16x32_bf16 v[42:45], v[166:169], v[190:193], 0
	v_mfma_f32_16x16x32_bf16 v[42:45], v[170:173], v[198:201], v[42:45]
	v_mfma_f32_16x16x32_bf16 v[26:29], v[166:169], v[202:205], 0
	v_mfma_f32_16x16x32_bf16 v[26:29], v[170:173], v[206:209], v[26:29]
	v_mfma_f32_16x16x32_bf16 v[10:13], v[166:169], v[210:213], 0
	v_mfma_f32_16x16x32_bf16 v[10:13], v[170:173], v[214:217], v[10:13]
	v_mfma_f32_16x16x32_bf16 v[54:57], v[174:177], v[182:185], 0
	v_mfma_f32_16x16x32_bf16 v[54:57], v[178:181], v[186:189], v[54:57]
	v_mfma_f32_16x16x32_bf16 v[38:41], v[174:177], v[190:193], 0
	v_mfma_f32_16x16x32_bf16 v[38:41], v[178:181], v[198:201], v[38:41]
	v_mfma_f32_16x16x32_bf16 v[22:25], v[174:177], v[202:205], 0
	v_mfma_f32_16x16x32_bf16 v[22:25], v[178:181], v[206:209], v[22:25]
	v_mfma_f32_16x16x32_bf16 v[6:9], v[174:177], v[210:213], 0
	v_mfma_f32_16x16x32_bf16 v[6:9], v[178:181], v[214:217], v[6:9]
	s_barrier
	s_add_i32 s46, 0, 0x18000
	v_add_u32_e32 v153, s46, v150
	s_add_i32 s47, 0, 0x1c000
	ds_read_b128 v[144:147], v153
	ds_read_b128 v[154:157], v153 offset:1024
	ds_read_b128 v[158:161], v153 offset:2048
	ds_read_b128 v[162:165], v153 offset:3072
	v_add_u32_e32 v153, s47, v150
	ds_read_b128 v[166:169], v153
	ds_read_b128 v[170:173], v153 offset:1024
	ds_read_b128 v[174:177], v153 offset:2048
	ds_read_b128 v[178:181], v153 offset:3072
	s_add_u32 s14, s14, 0x40000
	s_addc_u32 s15, s15, 0
	s_mov_b32 m0, s26
	v_lshl_add_u64 v[224:225], s[14:15], 0, v[2:3]
	ds_read_b128 v[182:185], v152 offset:32768
	ds_read_b128 v[186:189], v152 offset:33792
	ds_read_b128 v[190:193], v152 offset:34816
	ds_read_b128 v[198:201], v152 offset:35840
	ds_read_b128 v[202:205], v152 offset:36864
	ds_read_b128 v[206:209], v152 offset:37888
	ds_read_b128 v[210:213], v152 offset:38912
	ds_read_b128 v[214:217], v152 offset:39936
	global_load_lds_dwordx4 v[224:225], off
	v_lshl_add_u64 v[224:225], s[14:15], 0, v[136:137]
	s_mov_b32 m0, s27
	s_nop 0
	global_load_lds_dwordx4 v[224:225], off
	s_waitcnt vmcnt(8)
	s_waitcnt lgkmcnt(0)
	s_barrier
; #define PG8_STAGE(bufoff, gbase, voff) do { _Pragma("unroll") for (int _i = 0; _i < 2; ++_i) \
;         __builtin_amdgcn_global_load_lds((const unsigned*)((const char*)(gbase) + (voff)[_i]), (PG8_LAS unsigned*)(lds + (bufoff) + ldsw + _i * 8192), 16, 0, 0); } while (0)
; #define PG8_LDA(dst, b, h) do { _Pragma("unroll") for (int m = 0; m < 4; ++m) _Pragma("unroll") for (int k = 0; k < 2; ++k) dst[m][k] = *(const PG8_LAS bf16x8*)(lds + PG8_SA(b, h) + aoff + m * 2048 + k * 1024); } while (0)
; #define PG8_MMA(ai, bj, At, Bt) do { __builtin_amdgcn_s_setprio(1); _Pragma("unroll") for (int m = 0; m < 4; ++m) _Pragma("unroll") for (int n = 0; n < 2; ++n) _Pragma("unroll") for (int k = 0; k < 2; ++k) \
;         acc[ai][bj][m][n] = __builtin_amdgcn_mfma_f32_16x16x32_bf16(Bt[n][k], At[m][k], acc[ai][bj][m][n], 0, 0, 0); __builtin_amdgcn_s_setprio(0); } while (0)
; #define PG8_WAIT_V(n) asm volatile("s_waitcnt vmcnt(" #n ")" ::: "memory")
; #define PG8_WAIT_L(n) asm volatile("s_waitcnt lgkmcnt(" #n ")" ::: "memory")
; #define PG8_BAR __builtin_amdgcn_s_barrier()
; #define PG8_SCHED __builtin_amdgcn_sched_barrier(0)
; template <class Epi, class Sched, bool ALIGN_EPI = false, bool SP2 = false>
; __device__ __forceinline__ void gemm_phase(PG8_LAS unsigned char* lds, const Gemm g, const Sched& S, const Epi& E, const int tid_in) {
;     ...
;             PG8_WAIT_V(8); PG8_WAIT_L(0); PG8_BAR; PG8_MMA(0, 0, At, B0); PG8_MMA(0, 1, At, B1); PG8_BAR; PG8_SCHED;
;             PG8_LDA(At, 1, 1); PG8_STAGE(PG8_SB(1, 0), b3, voffB); PG8_STAGE(PG8_SB(1, 1), b3 + hstep, voffB); PG8_STAGE(PG8_SA(1, 0), a3, voffA);
;     __device__ __forceinline__ void operator()(const f32x4 (&acc)[2][2][4][2], const Unit& u, int wr, int wc, int fr, int fq) const {
;     ...
;             for (int m = 0; m < 4; ++m) rs[ai][m] = rowss[row0 + ai * HALF + m * 16];
	v_mfma_f32_16x16x32_bf16 v[130:133], v[144:147], v[182:185], v[130:133]
	v_mfma_f32_16x16x32_bf16 v[130:133], v[154:157], v[186:189], v[130:133]
	v_mfma_f32_16x16x32_bf16 v[114:117], v[144:147], v[190:193], v[114:117]
	v_mfma_f32_16x16x32_bf16 v[114:117], v[154:157], v[198:201], v[114:117]
	v_mfma_f32_16x16x32_bf16 v[98:101], v[144:147], v[202:205], v[98:101]
	v_mfma_f32_16x16x32_bf16 v[98:101], v[154:157], v[206:209], v[98:101]
	v_mfma_f32_16x16x32_bf16 v[82:85], v[144:147], v[210:213], v[82:85]
	v_mfma_f32_16x16x32_bf16 v[82:85], v[154:157], v[214:217], v[82:85]
	v_mfma_f32_16x16x32_bf16 v[126:129], v[158:161], v[182:185], v[126:129]
	v_mfma_f32_16x16x32_bf16 v[126:129], v[162:165], v[186:189], v[126:129]
	v_mfma_f32_16x16x32_bf16 v[110:113], v[158:161], v[190:193], v[110:113]
	v_mfma_f32_16x16x32_bf16 v[110:113], v[162:165], v[198:201], v[110:113]
	v_mfma_f32_16x16x32_bf16 v[94:97], v[158:161], v[202:205], v[94:97]
	v_mfma_f32_16x16x32_bf16 v[94:97], v[162:165], v[206:209], v[94:97]
	v_mfma_f32_16x16x32_bf16 v[78:81], v[158:161], v[210:213], v[78:81]
	v_mfma_f32_16x16x32_bf16 v[78:81], v[162:165], v[214:217], v[78:81]
	v_mfma_f32_16x16x32_bf16 v[122:125], v[166:169], v[182:185], v[122:125]
	v_mfma_f32_16x16x32_bf16 v[122:125], v[170:173], v[186:189], v[122:125]
	v_mfma_f32_16x16x32_bf16 v[106:109], v[166:169], v[190:193], v[106:109]
	v_mfma_f32_16x16x32_bf16 v[106:109], v[170:173], v[198:201], v[106:109]
	v_mfma_f32_16x16x32_bf16 v[90:93], v[166:169], v[202:205], v[90:93]
	v_mfma_f32_16x16x32_bf16 v[90:93], v[170:173], v[206:209], v[90:93]
	v_mfma_f32_16x16x32_bf16 v[74:77], v[166:169], v[210:213], v[74:77]
	v_mfma_f32_16x16x32_bf16 v[74:77], v[170:173], v[214:217], v[74:77]
	v_mfma_f32_16x16x32_bf16 v[118:121], v[174:177], v[182:185], v[118:121]
	v_mfma_f32_16x16x32_bf16 v[118:121], v[178:181], v[186:189], v[118:121]
	v_mfma_f32_16x16x32_bf16 v[102:105], v[174:177], v[190:193], v[102:105]
	v_mfma_f32_16x16x32_bf16 v[102:105], v[178:181], v[198:201], v[102:105]
	v_mfma_f32_16x16x32_bf16 v[86:89], v[174:177], v[202:205], v[86:89]
	v_mfma_f32_16x16x32_bf16 v[86:89], v[178:181], v[206:209], v[86:89]
	v_mfma_f32_16x16x32_bf16 v[70:73], v[174:177], v[210:213], v[70:73]
	v_mfma_f32_16x16x32_bf16 v[70:73], v[178:181], v[214:217], v[70:73]
	s_barrier
	s_add_i32 s14, s46, s19
	v_lshl_add_u64 v[148:149], v[148:149], 0, s[28:29]
	s_mov_b32 m0, s14
	ds_read_b128 v[182:185], v152 offset:49152
	ds_read_b128 v[186:189], v152 offset:50176
	ds_read_b128 v[190:193], v152 offset:51200
	ds_read_b128 v[198:201], v152 offset:52224
	ds_read_b128 v[202:205], v152 offset:53248
	ds_read_b128 v[206:209], v152 offset:54272
	ds_read_b128 v[210:213], v152 offset:55296
	ds_read_b128 v[214:217], v152 offset:56320
	global_load_lds_dwordx4 v[148:149], off
	s_add_i32 m0, s14, 0x2000
	s_add_u32 s12, s12, 0x40080
	v_lshl_add_u64 v[148:149], v[218:219], 0, s[28:29]
	s_addc_u32 s13, s13, 0
	s_add_i32 s14, s47, s19
	global_load_lds_dwordx4 v[148:149], off
	v_lshl_add_u64 v[148:149], s[12:13], 0, v[134:135]
	s_mov_b32 m0, s14
	s_nop 0
	global_load_lds_dwordx4 v[148:149], off
	v_lshl_add_u64 v[148:149], s[12:13], 0, v[138:139]
	s_add_i32 m0, s14, 0x2000
	s_nop 0
	global_load_lds_dwordx4 v[148:149], off
	v_lshl_add_u64 v[148:149], v[220:221], 0, s[28:29]
	s_mov_b32 m0, s30
	s_nop 0
	global_load_lds_dwordx4 v[148:149], off
	v_lshl_add_u64 v[148:149], v[222:223], 0, s[28:29]
	s_mov_b32 m0, s31
	s_nop 0
	global_load_lds_dwordx4 v[148:149], off
	s_waitcnt vmcnt(8)
	s_waitcnt lgkmcnt(0)
	s_cmp_lg_u32 s45, 12
	s_cbranch_scc1 .Lrs_in_skip_pin
	v_lshl_add_u32 v148, s38, 8, v5
	v_ashrrev_i32_e32 v149, 31, v148
	v_lshl_add_u64 v[148:149], v[148:149], 2, s[6:7]
	global_load_dword v226, v[148:149], off
	global_load_dword v227, v[148:149], off offset:64
	global_load_dword v228, v[148:149], off offset:128
	global_load_dword v229, v[148:149], off offset:192
	global_load_dword v238, v[148:149], off offset:512
	global_load_dword v239, v[148:149], off offset:576
	global_load_dword v240, v[148:149], off offset:640
	global_load_dword v241, v[148:149], off offset:704

; #define PG8_STAGE(bufoff, gbase, voff) do { _Pragma("unroll") for (int _i = 0; _i < 2; ++_i) \
;         __builtin_amdgcn_global_load_lds((const unsigned*)((const char*)(gbase) + (voff)[_i]), (PG8_LAS unsigned*)(lds + (bufoff) + ldsw + _i * 8192), 16, 0, 0); } while (0)
; #define PG8_LDA(dst, b, h) do { _Pragma("unroll") for (int m = 0; m < 4; ++m) _Pragma("unroll") for (int k = 0; k < 2; ++k) dst[m][k] = *(const PG8_LAS bf16x8*)(lds + PG8_SA(b, h) + aoff + m * 2048 + k * 1024); } while (0)
; #define PG8_LDB(dst, b, h) do { _Pragma("unroll") for (int n = 0; n < 2; ++n) _Pragma("unroll") for (int k = 0; k < 2; ++k) dst[n][k] = *(const PG8_LAS bf16x8*)(lds + PG8_SB(b, h) + boff + n * 2048 + k * 1024); } while (0)
; #define PG8_WAIT_V(n) asm volatile("s_waitcnt vmcnt(" #n ")" ::: "memory")
; #define PG8_WAIT_L(n) asm volatile("s_waitcnt lgkmcnt(" #n ")" ::: "memory")
; #define PG8_BAR __builtin_amdgcn_s_barrier()
; #define PG8_SCHED __builtin_amdgcn_sched_barrier(0)
; template <class Epi, class Sched, bool ALIGN_EPI = false, bool SP2 = false>
; __device__ __forceinline__ void gemm_phase(PG8_LAS unsigned char* lds, const Gemm g, const Sched& S, const Epi& E, const int tid_in) {
;     ...
;         const char* nA = has_next ? (const char*)g.A + (size_t)nxt.pm * tstep : cA; const char* nB = has_next ? (const char*)g.Bt + (size_t)nxt.pn * tstep : cB;
;         for (int t = 0; t < nt; t += 2) {
;             const bool last = (t == nt - 2);
;             const char* a1 = cA + (size_t)(t + 1) * kstep;
;             const char* a2 = last ? nA : cA + (size_t)(t + 2) * kstep; const char* b2 = last ? nB : cB + (size_t)(t + 2) * kstep;
;             const char* a3 = a2 + kstep; const char* b3 = b2 + kstep;
;             if (last && has_next) S.a_ready(nxt);
;             if constexpr (SP2) {
;             PG8_LDB(B0, 0, 0); PG8_LDB(B1, 0, 1); PG8_SCHED; PG8_LDA(At, 0, 0); PG8_STAGE(PG8_SA(1, 1), a1 + hstep, voffA);
;             PG8_WAIT_V(8); PG8_WAIT_L(0); PG8_BAR; PG8_MMA(0, 0, At, B0); PG8_MMA(0, 1, At, B1); PG8_BAR; PG8_SCHED;
;             PG8_LDA(At, 0, 1); PG8_STAGE(PG8_SB(0, 0), b2, voffB); PG8_STAGE(PG8_SB(0, 1), b2 + hstep, voffB); PG8_STAGE(PG8_SA(0, 0), a2, voffA);
;             PG8_WAIT_V(8); PG8_WAIT_L(0); PG8_BAR; PG8_MMA(1, 0, At, B0); PG8_MMA(1, 1, At, B1); PG8_BAR; PG8_SCHED;
.LBB0_153:
	s_ashr_i32 s25, s24, 31
	s_lshl_b64 s[14:15], s[24:25], 19
	s_add_u32 s34, s84, s14
	s_addc_u32 s35, s85, s15
	s_and_b64 s[14:15], s[36:37], exec
	s_cselect_b32 s25, s35, s11
	s_cselect_b32 s41, s34, s10
	s_ashr_i32 s21, s20, 31
	s_lshl_b64 s[14:15], s[20:21], 19
	s_add_u32 s38, s3, s14
	s_addc_u32 s39, s16, s15
	s_and_b64 s[14:15], s[36:37], exec
	s_cselect_b32 s21, s39, s13
	s_cselect_b32 s42, s38, s12
	s_add_u32 s10, s10, 0x40080
	s_addc_u32 s11, s11, 0
	s_add_u32 s43, s12, 0x100
	s_addc_u32 s44, s13, 0
	s_mov_b32 s45, -2
	s_add_u32 s12, s10, 0xfffc0080
	s_addc_u32 s13, s11, -1
	s_add_i32 s46, 0, 0x10000
	s_cmp_eq_u32 s45, 12
	s_cselect_b32 s15, s25, s13
	s_cselect_b32 s14, s41, s12
	v_add_u32_e32 v144, s46, v146
	s_cselect_b32 s13, s21, s44
	s_cselect_b32 s12, s42, s43
	s_add_i32 s48, 0, 0x14000
	ds_read_b128 v[150:153], v144
	ds_read_b128 v[154:157], v144 offset:1024
	ds_read_b128 v[158:161], v144 offset:2048
	ds_read_b128 v[162:165], v144 offset:3072
	v_add_u32_e32 v144, s48, v146
	ds_read_b128 v[166:169], v144
	ds_read_b128 v[170:173], v144 offset:1024
	ds_read_b128 v[174:177], v144 offset:2048
	ds_read_b128 v[178:181], v144 offset:3072
	v_lshl_add_u64 v[144:145], s[10:11], 0, v[140:141]
	s_add_i32 m0, s18, 0xc000
	ds_read_b128 v[182:185], v148
	ds_read_b128 v[186:189], v148 offset:1024
	ds_read_b128 v[190:193], v148 offset:2048
	ds_read_b128 v[198:201], v148 offset:3072
	ds_read_b128 v[202:205], v148 offset:4096
	ds_read_b128 v[206:209], v148 offset:5120
	ds_read_b128 v[210:213], v148 offset:6144
	ds_read_b128 v[214:217], v148 offset:7168
	global_load_lds_dwordx4 v[144:145], off
	v_lshl_add_u64 v[144:145], s[10:11], 0, v[142:143]
	s_add_i32 m0, s18, 0xe000
	s_nop 0
	global_load_lds_dwordx4 v[144:145], off
	s_nop 0
	s_waitcnt vmcnt(8)
	s_waitcnt lgkmcnt(0)
	s_barrier
	v_mfma_f32_16x16x32_bf16 v[130:133], v[150:153], v[182:185], 0
	v_mfma_f32_16x16x32_bf16 v[130:133], v[154:157], v[186:189], v[130:133]
	v_mfma_f32_16x16x32_bf16 v[114:117], v[150:153], v[190:193], 0
	v_mfma_f32_16x16x32_bf16 v[114:117], v[154:157], v[198:201], v[114:117]
	v_mfma_f32_16x16x32_bf16 v[98:101], v[150:153], v[202:205], 0
	v_mfma_f32_16x16x32_bf16 v[98:101], v[154:157], v[206:209], v[98:101]
	v_mfma_f32_16x16x32_bf16 v[82:85], v[150:153], v[210:213], 0
	v_mfma_f32_16x16x32_bf16 v[82:85], v[154:157], v[214:217], v[82:85]
	v_mfma_f32_16x16x32_bf16 v[126:129], v[158:161], v[182:185], 0
	v_mfma_f32_16x16x32_bf16 v[126:129], v[162:165], v[186:189], v[126:129]
	v_mfma_f32_16x16x32_bf16 v[106:109], v[158:161], v[190:193], 0
	v_mfma_f32_16x16x32_bf16 v[106:109], v[162:165], v[198:201], v[106:109]
	v_mfma_f32_16x16x32_bf16 v[94:97], v[158:161], v[202:205], 0
	v_mfma_f32_16x16x32_bf16 v[94:97], v[162:165], v[206:209], v[94:97]
	v_mfma_f32_16x16x32_bf16 v[78:81], v[158:161], v[210:213], 0
	v_mfma_f32_16x16x32_bf16 v[78:81], v[162:165], v[214:217], v[78:81]
	v_mfma_f32_16x16x32_bf16 v[122:125], v[166:169], v[182:185], 0
	v_mfma_f32_16x16x32_bf16 v[122:125], v[170:173], v[186:189], v[122:125]
	v_mfma_f32_16x16x32_bf16 v[110:113], v[166:169], v[190:193], 0
	v_mfma_f32_16x16x32_bf16 v[110:113], v[170:173], v[198:201], v[110:113]
	v_mfma_f32_16x16x32_bf16 v[90:93], v[166:169], v[202:205], 0
	v_mfma_f32_16x16x32_bf16 v[90:93], v[170:173], v[206:209], v[90:93]
	v_mfma_f32_16x16x32_bf16 v[74:77], v[166:169], v[210:213], 0
	v_mfma_f32_16x16x32_bf16 v[74:77], v[170:173], v[214:217], v[74:77]
	v_mfma_f32_16x16x32_bf16 v[118:121], v[174:177], v[182:185], 0
	v_mfma_f32_16x16x32_bf16 v[118:121], v[178:181], v[186:189], v[118:121]
	v_mfma_f32_16x16x32_bf16 v[102:105], v[174:177], v[190:193], 0
	v_mfma_f32_16x16x32_bf16 v[102:105], v[178:181], v[198:201], v[102:105]
	v_mfma_f32_16x16x32_bf16 v[86:89], v[174:177], v[202:205], 0
	v_mfma_f32_16x16x32_bf16 v[86:89], v[178:181], v[206:209], v[86:89]
	v_mfma_f32_16x16x32_bf16 v[70:73], v[174:177], v[210:213], 0
	v_mfma_f32_16x16x32_bf16 v[70:73], v[178:181], v[214:217], v[70:73]
	s_barrier
	s_add_i32 s46, s46, s17
	v_lshl_add_u64 v[144:145], s[12:13], 0, v[136:137]
	s_mov_b32 m0, s46
	ds_read_b128 v[182:185], v148 offset:16384
	ds_read_b128 v[186:189], v148 offset:17408
	ds_read_b128 v[190:193], v148 offset:18432
	ds_read_b128 v[198:201], v148 offset:19456
	ds_read_b128 v[202:205], v148 offset:20480
	ds_read_b128 v[206:209], v148 offset:21504
	ds_read_b128 v[210:213], v148 offset:22528
	ds_read_b128 v[214:217], v148 offset:23552
	global_load_lds_dwordx4 v[144:145], off
	s_add_i32 m0, s46, 0x2000
	s_add_u32 s46, s12, 0x40000
	v_lshl_add_u64 v[218:219], s[12:13], 0, v[2:3]
	s_addc_u32 s47, s13, 0
	s_add_i32 s48, s48, s17
	global_load_lds_dwordx4 v[218:219], off
	v_lshl_add_u64 v[220:221], s[46:47], 0, v[136:137]
	s_mov_b32 m0, s48
	v_lshl_add_u64 v[222:223], s[14:15], 0, v[134:135]
	global_load_lds_dwordx4 v[220:221], off
	v_lshl_add_u64 v[220:221], s[46:47], 0, v[2:3]
	s_add_i32 m0, s48, 0x2000
	s_nop 0
	global_load_lds_dwordx4 v[220:221], off
	v_lshl_add_u64 v[220:221], s[14:15], 0, v[138:139]
	s_mov_b32 m0, s18
	s_nop 0
	global_load_lds_dwordx4 v[220:221], off
	s_mov_b32 m0, s19
	s_nop 0
	global_load_lds_dwordx4 v[222:223], off
	s_cmp_lt_u32 s30, 2
	s_cbranch_scc1 .Lpwgu_first
	s_waitcnt vmcnt(16)
	s_branch .Lpwgu_j

; #define PG8_STAGE(bufoff, gbase, voff) do { _Pragma("unroll") for (int _i = 0; _i < 2; ++_i) \
;         __builtin_amdgcn_global_load_lds((const unsigned*)((const char*)(gbase) + (voff)[_i]), (PG8_LAS unsigned*)(lds + (bufoff) + ldsw + _i * 8192), 16, 0, 0); } while (0)
; #define PG8_LDA(dst, b, h) do { _Pragma("unroll") for (int m = 0; m < 4; ++m) _Pragma("unroll") for (int k = 0; k < 2; ++k) dst[m][k] = *(const PG8_LAS bf16x8*)(lds + PG8_SA(b, h) + aoff + m * 2048 + k * 1024); } while (0)
; #define PG8_LDB(dst, b, h) do { _Pragma("unroll") for (int n = 0; n < 2; ++n) _Pragma("unroll") for (int k = 0; k < 2; ++k) dst[n][k] = *(const PG8_LAS bf16x8*)(lds + PG8_SB(b, h) + boff + n * 2048 + k * 1024); } while (0)
; #define PG8_MMA(ai, bj, At, Bt) do { __builtin_amdgcn_s_setprio(1); _Pragma("unroll") for (int m = 0; m < 4; ++m) _Pragma("unroll") for (int n = 0; n < 2; ++n) _Pragma("unroll") for (int k = 0; k < 2; ++k) \
;         acc[ai][bj][m][n] = __builtin_amdgcn_mfma_f32_16x16x32_bf16(Bt[n][k], At[m][k], acc[ai][bj][m][n], 0, 0, 0); __builtin_amdgcn_s_setprio(0); } while (0)
; #define PG8_WAIT_V(n) asm volatile("s_waitcnt vmcnt(" #n ")" ::: "memory")
; #define PG8_WAIT_L(n) asm volatile("s_waitcnt lgkmcnt(" #n ")" ::: "memory")
; #define PG8_BAR __builtin_amdgcn_s_barrier()
; #define PG8_SCHED __builtin_amdgcn_sched_barrier(0)
; template <class Epi, class Sched, bool ALIGN_EPI = false, bool SP2 = false>
; __device__ __forceinline__ void gemm_phase(PG8_LAS unsigned char* lds, const Gemm g, const Sched& S, const Epi& E, const int tid_in) {
;     ...
;             PG8_WAIT_V(8); PG8_WAIT_L(0); PG8_BAR; PG8_MMA(1, 0, At, B0); PG8_MMA(1, 1, At, B1); PG8_BAR; PG8_SCHED;
;             PG8_LDB(B0, 1, 0); PG8_LDB(B1, 1, 1); PG8_SCHED; PG8_LDA(At, 1, 0); PG8_STAGE(PG8_SA(0, 1), a2 + hstep, voffA);
;             PG8_WAIT_V(8); PG8_WAIT_L(0); PG8_BAR; PG8_MMA(0, 0, At, B0); PG8_MMA(0, 1, At, B1); PG8_BAR; PG8_SCHED;
.Lpwgu_j:
	s_waitcnt lgkmcnt(0)
	s_barrier
	v_mfma_f32_16x16x32_bf16 v[66:69], v[150:153], v[182:185], 0
	v_mfma_f32_16x16x32_bf16 v[66:69], v[154:157], v[186:189], v[66:69]
	v_mfma_f32_16x16x32_bf16 v[50:53], v[150:153], v[190:193], 0
	v_mfma_f32_16x16x32_bf16 v[50:53], v[154:157], v[198:201], v[50:53]
	v_mfma_f32_16x16x32_bf16 v[34:37], v[150:153], v[202:205], 0
	v_mfma_f32_16x16x32_bf16 v[34:37], v[154:157], v[206:209], v[34:37]
	v_mfma_f32_16x16x32_bf16 v[18:21], v[150:153], v[210:213], 0
	v_mfma_f32_16x16x32_bf16 v[18:21], v[154:157], v[214:217], v[18:21]
	v_mfma_f32_16x16x32_bf16 v[62:65], v[158:161], v[182:185], 0
	v_mfma_f32_16x16x32_bf16 v[62:65], v[162:165], v[186:189], v[62:65]
	v_mfma_f32_16x16x32_bf16 v[46:49], v[158:161], v[190:193], 0
	v_mfma_f32_16x16x32_bf16 v[46:49], v[162:165], v[198:201], v[46:49]
	v_mfma_f32_16x16x32_bf16 v[30:33], v[158:161], v[202:205], 0
	v_mfma_f32_16x16x32_bf16 v[30:33], v[162:165], v[206:209], v[30:33]
	v_mfma_f32_16x16x32_bf16 v[14:17], v[158:161], v[210:213], 0
	v_mfma_f32_16x16x32_bf16 v[14:17], v[162:165], v[214:217], v[14:17]
	v_mfma_f32_16x16x32_bf16 v[58:61], v[166:169], v[182:185], 0
	v_mfma_f32_16x16x32_bf16 v[58:61], v[170:173], v[186:189], v[58:61]
	v_mfma_f32_16x16x32_bf16 v[42:45], v[166:169], v[190:193], 0
	v_mfma_f32_16x16x32_bf16 v[42:45], v[170:173], v[198:201], v[42:45]
	v_mfma_f32_16x16x32_bf16 v[26:29], v[166:169], v[202:205], 0
	v_mfma_f32_16x16x32_bf16 v[26:29], v[170:173], v[206:209], v[26:29]
	v_mfma_f32_16x16x32_bf16 v[10:13], v[166:169], v[210:213], 0
	v_mfma_f32_16x16x32_bf16 v[10:13], v[170:173], v[214:217], v[10:13]
	v_mfma_f32_16x16x32_bf16 v[54:57], v[174:177], v[182:185], 0
	v_mfma_f32_16x16x32_bf16 v[54:57], v[178:181], v[186:189], v[54:57]
	v_mfma_f32_16x16x32_bf16 v[38:41], v[174:177], v[190:193], 0
	v_mfma_f32_16x16x32_bf16 v[38:41], v[178:181], v[198:201], v[38:41]
	v_mfma_f32_16x16x32_bf16 v[22:25], v[174:177], v[202:205], 0
	v_mfma_f32_16x16x32_bf16 v[22:25], v[178:181], v[206:209], v[22:25]
	v_mfma_f32_16x16x32_bf16 v[6:9], v[174:177], v[210:213], 0
	v_mfma_f32_16x16x32_bf16 v[6:9], v[178:181], v[214:217], v[6:9]
	s_barrier
	s_add_i32 s46, 0, 0x18000
	v_add_u32_e32 v149, s46, v146
	s_add_i32 s47, 0, 0x1c000
	ds_read_b128 v[150:153], v149
	ds_read_b128 v[154:157], v149 offset:1024
	ds_read_b128 v[158:161], v149 offset:2048
	ds_read_b128 v[162:165], v149 offset:3072
	v_add_u32_e32 v149, s47, v146
	ds_read_b128 v[166:169], v149
	ds_read_b128 v[170:173], v149 offset:1024
	ds_read_b128 v[174:177], v149 offset:2048
	ds_read_b128 v[178:181], v149 offset:3072
	s_add_u32 s14, s14, 0x40000
	s_addc_u32 s15, s15, 0
	s_mov_b32 m0, s22
	v_lshl_add_u64 v[224:225], s[14:15], 0, v[138:139]
	ds_read_b128 v[182:185], v148 offset:32768
	ds_read_b128 v[186:189], v148 offset:33792
	ds_read_b128 v[190:193], v148 offset:34816
	ds_read_b128 v[198:201], v148 offset:35840
	ds_read_b128 v[202:205], v148 offset:36864
	ds_read_b128 v[206:209], v148 offset:37888
	ds_read_b128 v[210:213], v148 offset:38912
	ds_read_b128 v[214:217], v148 offset:39936
	global_load_lds_dwordx4 v[224:225], off
	v_lshl_add_u64 v[224:225], s[14:15], 0, v[134:135]
	s_mov_b32 m0, s23
	s_nop 0
	global_load_lds_dwordx4 v[224:225], off
	s_waitcnt vmcnt(8)
	s_waitcnt lgkmcnt(0)
	s_barrier
; #define PG8_STAGE(bufoff, gbase, voff) do { _Pragma("unroll") for (int _i = 0; _i < 2; ++_i) \
;         __builtin_amdgcn_global_load_lds((const unsigned*)((const char*)(gbase) + (voff)[_i]), (PG8_LAS unsigned*)(lds + (bufoff) + ldsw + _i * 8192), 16, 0, 0); } while (0)
; #define PG8_LDA(dst, b, h) do { _Pragma("unroll") for (int m = 0; m < 4; ++m) _Pragma("unroll") for (int k = 0; k < 2; ++k) dst[m][k] = *(const PG8_LAS bf16x8*)(lds + PG8_SA(b, h) + aoff + m * 2048 + k * 1024); } while (0)
; #define PG8_MMA(ai, bj, At, Bt) do { __builtin_amdgcn_s_setprio(1); _Pragma("unroll") for (int m = 0; m < 4; ++m) _Pragma("unroll") for (int n = 0; n < 2; ++n) _Pragma("unroll") for (int k = 0; k < 2; ++k) \
;         acc[ai][bj][m][n] = __builtin_amdgcn_mfma_f32_16x16x32_bf16(Bt[n][k], At[m][k], acc[ai][bj][m][n], 0, 0, 0); __builtin_amdgcn_s_setprio(0); } while (0)
; #define PG8_WAIT_V(n) asm volatile("s_waitcnt vmcnt(" #n ")" ::: "memory")
; #define PG8_WAIT_L(n) asm volatile("s_waitcnt lgkmcnt(" #n ")" ::: "memory")
; #define PG8_BAR __builtin_amdgcn_s_barrier()
; #define PG8_SCHED __builtin_amdgcn_sched_barrier(0)
; template <class Epi, class Sched, bool ALIGN_EPI = false, bool SP2 = false>
; __device__ __forceinline__ void gemm_phase(PG8_LAS unsigned char* lds, const Gemm g, const Sched& S, const Epi& E, const int tid_in) {
;     ...
;             PG8_WAIT_V(8); PG8_WAIT_L(0); PG8_BAR; PG8_MMA(0, 0, At, B0); PG8_MMA(0, 1, At, B1); PG8_BAR; PG8_SCHED;
;             PG8_LDA(At, 1, 1); PG8_STAGE(PG8_SB(1, 0), b3, voffB); PG8_STAGE(PG8_SB(1, 1), b3 + hstep, voffB); PG8_STAGE(PG8_SA(1, 0), a3, voffA);
;     __device__ __forceinline__ void operator()(const f32x4 (&acc)[2][2][4][2], const Unit& u, int wr, int wc, int fr, int fq) const {
;     ...
;             for (int m = 0; m < 4; ++m) rs[ai][m] = rowss[row0 + ai * HALF + m * 16];
	v_mfma_f32_16x16x32_bf16 v[130:133], v[150:153], v[182:185], v[130:133]
	v_mfma_f32_16x16x32_bf16 v[130:133], v[154:157], v[186:189], v[130:133]
	v_mfma_f32_16x16x32_bf16 v[114:117], v[150:153], v[190:193], v[114:117]
	v_mfma_f32_16x16x32_bf16 v[114:117], v[154:157], v[198:201], v[114:117]
	v_mfma_f32_16x16x32_bf16 v[98:101], v[150:153], v[202:205], v[98:101]
	v_mfma_f32_16x16x32_bf16 v[98:101], v[154:157], v[206:209], v[98:101]
	v_mfma_f32_16x16x32_bf16 v[82:85], v[150:153], v[210:213], v[82:85]
	v_mfma_f32_16x16x32_bf16 v[82:85], v[154:157], v[214:217], v[82:85]
	v_mfma_f32_16x16x32_bf16 v[126:129], v[158:161], v[182:185], v[126:129]
	v_mfma_f32_16x16x32_bf16 v[126:129], v[162:165], v[186:189], v[126:129]
	v_mfma_f32_16x16x32_bf16 v[106:109], v[158:161], v[190:193], v[106:109]
	v_mfma_f32_16x16x32_bf16 v[106:109], v[162:165], v[198:201], v[106:109]
	v_mfma_f32_16x16x32_bf16 v[94:97], v[158:161], v[202:205], v[94:97]
	v_mfma_f32_16x16x32_bf16 v[94:97], v[162:165], v[206:209], v[94:97]
	v_mfma_f32_16x16x32_bf16 v[78:81], v[158:161], v[210:213], v[78:81]
	v_mfma_f32_16x16x32_bf16 v[78:81], v[162:165], v[214:217], v[78:81]
	v_mfma_f32_16x16x32_bf16 v[122:125], v[166:169], v[182:185], v[122:125]
	v_mfma_f32_16x16x32_bf16 v[122:125], v[170:173], v[186:189], v[122:125]
	v_mfma_f32_16x16x32_bf16 v[110:113], v[166:169], v[190:193], v[110:113]
	v_mfma_f32_16x16x32_bf16 v[110:113], v[170:173], v[198:201], v[110:113]
	v_mfma_f32_16x16x32_bf16 v[90:93], v[166:169], v[202:205], v[90:93]
	v_mfma_f32_16x16x32_bf16 v[90:93], v[170:173], v[206:209], v[90:93]
	v_mfma_f32_16x16x32_bf16 v[74:77], v[166:169], v[210:213], v[74:77]
	v_mfma_f32_16x16x32_bf16 v[74:77], v[170:173], v[214:217], v[74:77]
	v_mfma_f32_16x16x32_bf16 v[118:121], v[174:177], v[182:185], v[118:121]
	v_mfma_f32_16x16x32_bf16 v[118:121], v[178:181], v[186:189], v[118:121]
	v_mfma_f32_16x16x32_bf16 v[102:105], v[174:177], v[190:193], v[102:105]
	v_mfma_f32_16x16x32_bf16 v[102:105], v[178:181], v[198:201], v[102:105]
	v_mfma_f32_16x16x32_bf16 v[86:89], v[174:177], v[202:205], v[86:89]
	v_mfma_f32_16x16x32_bf16 v[86:89], v[178:181], v[206:209], v[86:89]
	v_mfma_f32_16x16x32_bf16 v[70:73], v[174:177], v[210:213], v[70:73]
	v_mfma_f32_16x16x32_bf16 v[70:73], v[178:181], v[214:217], v[70:73]
	s_barrier
	s_add_i32 s14, s46, s17
	v_lshl_add_u64 v[144:145], v[144:145], 0, s[28:29]
	s_mov_b32 m0, s14
	ds_read_b128 v[182:185], v148 offset:49152
	ds_read_b128 v[186:189], v148 offset:50176
	ds_read_b128 v[190:193], v148 offset:51200
	ds_read_b128 v[198:201], v148 offset:52224
	ds_read_b128 v[202:205], v148 offset:53248
	ds_read_b128 v[206:209], v148 offset:54272
	ds_read_b128 v[210:213], v148 offset:55296
	ds_read_b128 v[214:217], v148 offset:56320
	global_load_lds_dwordx4 v[144:145], off
	s_add_i32 m0, s14, 0x2000
	s_add_u32 s12, s12, 0x40080
	v_lshl_add_u64 v[144:145], v[218:219], 0, s[28:29]
	s_addc_u32 s13, s13, 0
	s_add_i32 s14, s47, s17
	global_load_lds_dwordx4 v[144:145], off
	v_lshl_add_u64 v[144:145], s[12:13], 0, v[136:137]
	s_mov_b32 m0, s14
	s_nop 0
	global_load_lds_dwordx4 v[144:145], off
	v_lshl_add_u64 v[144:145], s[12:13], 0, v[2:3]
	s_add_i32 m0, s14, 0x2000
	s_nop 0
	global_load_lds_dwordx4 v[144:145], off
	v_lshl_add_u64 v[144:145], v[220:221], 0, s[28:29]
	s_mov_b32 m0, s26
	s_nop 0
	global_load_lds_dwordx4 v[144:145], off
	v_lshl_add_u64 v[144:145], v[222:223], 0, s[28:29]
	s_mov_b32 m0, s27
	s_nop 0
	global_load_lds_dwordx4 v[144:145], off
	s_waitcnt vmcnt(8)
	s_waitcnt lgkmcnt(0)
	s_cmp_lg_u32 s45, 12
	s_cbranch_scc1 .Lrs_gu_skip_pgu
	v_lshl_add_u32 v144, s40, 8, v5
	v_ashrrev_i32_e32 v145, 31, v144
	v_lshl_add_u64 v[144:145], v[144:145], 2, s[6:7]
	global_load_dword v226, v[144:145], off
	global_load_dword v227, v[144:145], off offset:64
	global_load_dword v228, v[144:145], off offset:128
	global_load_dword v229, v[144:145], off offset:192
	global_load_dword v238, v[144:145], off offset:512
	global_load_dword v239, v[144:145], off offset:576
	global_load_dword v240, v[144:145], off offset:640
	global_load_dword v241, v[144:145], off offset:704
